# PEER gather start offsets in four groups per XCD (0 / 2.5 / 5 / 7.5 us by block index bits 3-4) instead of two
# speedup vs baseline: 1.1301x; 1.0004x over previous
.LBB0_1540:
	s_or_b64 exec, exec, s[0:1]
	v_mov_b32_e32 v36, v190
	s_waitcnt lgkmcnt(0)
	s_barrier
	v_readlane_b32 s98, v240, 10
	s_nop 0
	s_bfe_u32 s98, s98, 0x20003
	s_mul_i32 s98, s98, 1
	s_cmp_eq_u32 s98, 0
	s_cbranch_scc1 .Ldsk_a

.LBB0_2758:
	s_or_b64 exec, exec, s[0:1]
	s_waitcnt lgkmcnt(0)
	s_barrier
	v_readlane_b32 s98, v240, 10
	s_nop 0
	s_bfe_u32 s98, s98, 0x20003
	s_mul_i32 s98, s98, 1
	s_cmp_eq_u32 s98, 0
	s_cbranch_scc1 .Ldsk_b
